# v030 + attention prologues: first-tile wait/LDS staging/barrier moved below the lane-constant mask and accumulator setup so the setup overlaps the first K/V loads (7 sites)
# baseline (speedup 1.0000x reference)
; #define LAS __attribute__((address_space(3)))
; template <bool HAS_POST, class MaskF>
; __device__ __forceinline__ void attn_run(LAS unsigned char* lds, const bf16* Kg, const bf16* Vg, int pitch, int t0, int t1,
;                                          const bf16x8 (&qr)[4], f32x16& o0, f32x16& o1, f32x16& o2, MaskF& mf, const int wv) {
;     ...
;     if (t0 >= t1) return;
;     const int lrow = tid >> 3, lch = tid & 7;
;     const unsigned kwoff = lrow * 144 + lch * 16;
;     const unsigned vwoff = ATT_V0 + lrow * 128 + (((lch >> 1) ^ (((lrow >> 1) & 1) << 1)) * 32) + (lch & 1) * 16;
;     const bf16* kp = Kg + (size_t)(64 * t0 + lrow) * pitch + lch * 8;
;     const bf16* vp = Vg + (size_t)(64 * t0 + lrow) * pitch + lch * 8;
;     const size_t tstride = (size_t)64 * pitch;
;     const v4u z4 = (v4u){0u, 0u, 0u, 0u};
;     v4u kreg0 = *(const v4u*)kp, kreg1 = z4, vreg0 = *(const v4u*)vp, vreg1 = z4;
;     if (t0 + 1 < t1) { kreg1 = *(const v4u*)(kp + tstride); vreg1 = *(const v4u*)(vp + tstride); }
;     *(LAS v4u*)(lds + kwoff) = kreg0; *(LAS v4u*)(lds + KBUF + kwoff) = kreg1;
;     *(LAS v4u*)(lds + vwoff) = vreg0; *(LAS v4u*)(lds + VBUF + vwoff) = vreg1;
;     __syncthreads();
;     ACtx cx; cx.lds = lds; cx.kroff = r32 * 144 + hi * 16;
;     { const int gi = lane & 15, dsub = (lane >> 4) & 1, q4 = gi >> 2;
;       cx.vro0 = ATT_V0 + (4 * hi + q4) * 128 + (((0 + dsub) ^ (q4 & 2)) * 32) + (gi & 3) * 8;
;       cx.vro1 = ATT_V0 + (4 * hi + q4) * 128 + (((2 + dsub) ^ (q4 & 2)) * 32) + (gi & 3) * 8; }
;     if (wv >= 4) __builtin_amdgcn_s_setprio(1);
;     const short one_b = (r32 == 0) ? (short)0x3F80 : (short)0;
;     const bf16x8 ones = (bf16x8){one_b, one_b, one_b, one_b, one_b, one_b, one_b, one_b};
.LBB0_847:
	v_lshrrev_b32_e32 v6, 1, v6
	v_lshrrev_b32_e32 v7, 3, v4
	s_movk_i32 s0, 0x90
	v_bitop3_b32 v6, v6, v7, 2 bitop3:0x78
	v_lshlrev_b32_e32 v7, 4, v4
	v_mul_lo_u32 v1, v0, s0
	v_lshlrev_b32_e32 v0, 7, v0
	v_lshlrev_b32_e32 v6, 5, v6
	v_and_b32_e32 v7, 16, v7
	v_readlane_b32 s0, v253, 63
	v_or3_b32 v0, v0, v6, v7
	v_readlane_b32 s1, v254, 0
	v_add3_u32 v114, v1, v114, 0
	v_add_u32_e32 v163, 0, v0
	s_andn2_b64 vcc, exec, s[0:1]
	s_waitcnt lgkmcnt(0)
.LBB0_849:
	v_and_b32_e32 v0, 31, v4
	v_cmp_eq_u32_e32 vcc, 0, v0
	v_mul_u32_u24_e32 v6, 0x90, v0
	s_mov_b32 s0, 0x5040100
	v_cndmask_b32_e32 v0, 0, v249, vcc
	v_bfe_u32 v1, v4, 5, 1
	v_bfe_u32 v8, v4, 4, 1
	v_lshrrev_b32_e32 v9, 2, v5
	v_lshlrev_b32_e32 v5, 5, v5
	v_lshlrev_b32_e32 v4, 3, v4
	v_perm_b32 v98, v0, v0, s0
	v_add3_u32 v0, v153, v3, v2
	s_movk_i32 s0, 0x104
	v_lshlrev_b32_e32 v7, 4, v1
	v_lshlrev_b32_e32 v1, 9, v1
	v_and_b32_e32 v5, 0x180, v5
	v_and_or_b32 v10, v9, 2, v8
	v_and_b32_e32 v165, 24, v4
	v_bitop3_b32 v4, v8, v9, 2 bitop3:0x72
	v_mul_lo_u32 v0, v0, s0
	s_mov_b32 s16, 2
	v_lshlrev_b32_e32 v164, 5, v10
	v_lshlrev_b32_e32 v166, 5, v4
	s_mov_b32 s17, 0
	v_add3_u32 v167, 0, v6, v7
	v_mov_b32_e32 v99, v98
	v_mov_b32_e32 v100, v98
	v_mov_b32_e32 v101, v98
	v_add3_u32 v168, 0, v5, v1
	v_lshlrev_b32_e32 v169, 2, v159
	v_add_u32_e32 v170, 0, v0
	v_lshl_add_u32 v171, v159, 6, v242
	v_or_b32_e32 v172, 20, v159
	v_mov_b32_e32 v34, v32
	v_mov_b32_e32 v35, v32
	v_mov_b32_e32 v36, v32
	v_mov_b32_e32 v37, v32
	v_mov_b32_e32 v38, v32
	v_mov_b32_e32 v39, v32
	v_mov_b32_e32 v40, v32
	v_mov_b32_e32 v41, v32
	v_mov_b32_e32 v42, v32
	v_mov_b32_e32 v43, v32
	v_mov_b32_e32 v44, v32
	v_mov_b32_e32 v45, v32
	v_mov_b32_e32 v46, v32
	v_mov_b32_e32 v47, v32
	v_mov_b32_e32 v48, v32
	v_mov_b32_e32 v49, v32
	v_mov_b32_e32 v0, v162
	v_mov_b32_e32 v1, v162
	v_mov_b32_e32 v2, v162
	v_mov_b32_e32 v3, v162
	v_mov_b32_e32 v4, v162
	v_mov_b32_e32 v5, v162
	v_mov_b32_e32 v6, v162
	v_mov_b32_e32 v7, v162
	v_mov_b32_e32 v8, v162
	v_mov_b32_e32 v9, v162
	v_mov_b32_e32 v10, v162
	v_mov_b32_e32 v11, v162
	v_mov_b32_e32 v12, v162
	v_mov_b32_e32 v13, v162
	v_mov_b32_e32 v14, v162
	v_mov_b32_e32 v15, v162
	v_mov_b32_e32 v16, v161
	v_mov_b32_e32 v17, v161
	v_mov_b32_e32 v18, v161
	v_mov_b32_e32 v19, v161
	v_mov_b32_e32 v20, v161
	v_mov_b32_e32 v21, v161
	v_mov_b32_e32 v22, v161
	v_mov_b32_e32 v23, v161
	v_mov_b32_e32 v24, v161
	v_mov_b32_e32 v25, v161
	v_mov_b32_e32 v26, v161
	v_mov_b32_e32 v27, v161
	v_mov_b32_e32 v28, v161
	v_mov_b32_e32 v29, v161
	v_mov_b32_e32 v30, v161
	v_mov_b32_e32 v31, v161
	s_waitcnt vmcnt(0)
	ds_write_b128 v114, v[82:85]
	ds_write_b128 v114, v[90:93] offset:9216
	s_waitcnt vmcnt(0)
	ds_write_b128 v163, v[86:89] offset:36864
	ds_write_b128 v163, v[94:97] offset:45056
	s_waitcnt lgkmcnt(0)
	s_barrier
	global_load_dwordx4 v[212:215], v[210:211], off
	global_load_dwordx4 v[216:219], v[210:211], off offset:32
	global_load_dwordx4 v[220:223], v[210:211], off offset:64
	global_load_dwordx4 v[224:227], v[210:211], off offset:96
	s_and_b64 vcc, exec, s[24:25]
	s_cbranch_vccnz .Llb_6
	s_setprio 1
.Llb_6:
	s_branch .LBB0_851
.LBB0_850:
	v_add_u32_e32 v170, 0x80, v170
	v_add_u32_e32 v171, 0x800, v171
	s_addk_i32 s17, 0x80
	v_add_u32_e32 v172, 32, v172
	s_add_i32 s16, s16, 2
	s_and_b64 vcc, exec, s[12:13]
	s_waitcnt lgkmcnt(0)
	s_barrier
	s_cbranch_vccnz .LBB0_877

; #define LAS __attribute__((address_space(3)))
; __device__ __forceinline__ int crow(int r, int hi) { return (r & 3) + 8 * (r >> 2) + 4 * hi; }
; template <bool HAS_POST, class MaskF>
; __device__ __forceinline__ void attn_run(LAS unsigned char* lds, const bf16* Kg, const bf16* Vg, int pitch, int t0, int t1,
;                                          const bf16x8 (&qr)[4], f32x16& o0, f32x16& o1, f32x16& o2, MaskF& mf, const int wv) {
;     ...
;     if (t0 >= t1) return;
;     const int lrow = tid >> 3, lch = tid & 7;
;     const unsigned kwoff = lrow * 144 + lch * 16;
;     const unsigned vwoff = ATT_V0 + lrow * 128 + (((lch >> 1) ^ (((lrow >> 1) & 1) << 1)) * 32) + (lch & 1) * 16;
;     const bf16* kp = Kg + (size_t)(64 * t0 + lrow) * pitch + lch * 8;
;     const bf16* vp = Vg + (size_t)(64 * t0 + lrow) * pitch + lch * 8;
;     const size_t tstride = (size_t)64 * pitch;
;     const v4u z4 = (v4u){0u, 0u, 0u, 0u};
;     v4u kreg0 = *(const v4u*)kp, kreg1 = z4, vreg0 = *(const v4u*)vp, vreg1 = z4;
;     if (t0 + 1 < t1) { kreg1 = *(const v4u*)(kp + tstride); vreg1 = *(const v4u*)(vp + tstride); }
;     *(LAS v4u*)(lds + kwoff) = kreg0; *(LAS v4u*)(lds + KBUF + kwoff) = kreg1;
;     *(LAS v4u*)(lds + vwoff) = vreg0; *(LAS v4u*)(lds + VBUF + vwoff) = vreg1;
;     __syncthreads();
;     ACtx cx; cx.lds = lds; cx.kroff = r32 * 144 + hi * 16;
;     { const int gi = lane & 15, dsub = (lane >> 4) & 1, q4 = gi >> 2;
;       cx.vro0 = ATT_V0 + (4 * hi + q4) * 128 + (((0 + dsub) ^ (q4 & 2)) * 32) + (gi & 3) * 8;
;       cx.vro1 = ATT_V0 + (4 * hi + q4) * 128 + (((2 + dsub) ^ (q4 & 2)) * 32) + (gi & 3) * 8; }
;     if (wv >= 4) __builtin_amdgcn_s_setprio(1);
;     const short one_b = (r32 == 0) ? (short)0x3F80 : (short)0;
;     const bf16x8 ones = (bf16x8){one_b, one_b, one_b, one_b, one_b, one_b, one_b, one_b};
;     __device__ __forceinline__ void apply(int t, f32x16& p0, f32x16& p1) const {
;         if (t == c) {
; #pragma unroll
;             for (int r = 0; r < 16; ++r) { const int kv = crow(r, hi); if (kv > tq) p0[r] = NEGBIG; if (kv + 32 > tq) p1[r] = NEGBIG; }
;         }
.LBB0_918:
	v_lshrrev_b32_e32 v3, 1, v3
	v_lshrrev_b32_e32 v5, 3, v0
	s_movk_i32 s0, 0x90
	v_bitop3_b32 v3, v3, v5, 2 bitop3:0x78
	v_lshlrev_b32_e32 v5, 4, v0
	v_mul_lo_u32 v4, v2, s0
	v_lshlrev_b32_e32 v2, 7, v2
	v_lshlrev_b32_e32 v3, 5, v3
	v_and_b32_e32 v5, 16, v5
	v_readlane_b32 s0, v253, 63
	v_or3_b32 v2, v2, v3, v5
	v_readlane_b32 s1, v254, 0
	v_add3_u32 v161, v4, v114, 0
	v_add_u32_e32 v162, 0, v2
	s_andn2_b64 vcc, exec, s[0:1]
	s_waitcnt lgkmcnt(0)
.LBB0_920:
	v_and_b32_e32 v2, 31, v0
	v_bfe_u32 v3, v0, 5, 1
	v_bfe_u32 v6, v0, 4, 1
	v_lshrrev_b32_e32 v7, 2, v1
	v_lshlrev_b32_e32 v0, 3, v0
	v_and_b32_e32 v164, 24, v0
	v_bitop3_b32 v0, v6, v7, 2 bitop3:0x72
	v_cmp_eq_u32_e32 vcc, 0, v2
	v_lshlrev_b32_e32 v1, 5, v1
	v_lshlrev_b32_e32 v165, 5, v0
	v_cndmask_b32_e32 v0, 0, v249, vcc
	s_mov_b32 s0, 0x5040100
	v_lshlrev_b32_e32 v5, 4, v3
	v_lshlrev_b32_e32 v3, 9, v3
	v_and_b32_e32 v1, 0x180, v1
	v_perm_b32 v98, v0, v0, s0
	v_lshlrev_b32_e32 v0, 2, v159
	v_add3_u32 v167, 0, v1, v3
	v_or_b32_e32 v1, 32, v0
	v_cmp_gt_u32_e64 s[8:9], v1, v158
	v_or_b32_e32 v1, 33, v0
	v_cmp_gt_u32_e64 s[12:13], v1, v158
	v_or_b32_e32 v1, 2, v0
	v_cmp_gt_u32_e64 s[14:15], v1, v158
	v_or_b32_e32 v1, 34, v0
	v_cmp_gt_u32_e64 s[16:17], v1, v158
	v_or_b32_e32 v1, 3, v0
	v_cmp_gt_u32_e64 s[40:41], v1, v158
	v_or_b32_e32 v1, 35, v0
	v_cmp_gt_u32_e64 s[42:43], v1, v158
	v_or_b32_e32 v1, 8, v0
	v_cmp_gt_u32_e64 s[44:45], v1, v158
	v_or_b32_e32 v1, 40, v0
	v_cmp_gt_u32_e64 s[46:47], v1, v158
	v_or_b32_e32 v1, 9, v0
	v_cmp_gt_u32_e64 s[48:49], v1, v158
	v_or_b32_e32 v1, 41, v0
	v_cmp_gt_u32_e64 s[50:51], v1, v158
	v_or_b32_e32 v1, 10, v0
	v_cmp_gt_u32_e64 s[52:53], v1, v158
	v_or_b32_e32 v1, 42, v0
	v_cmp_gt_u32_e64 s[54:55], v1, v158
	v_or_b32_e32 v1, 11, v0
	v_cmp_gt_u32_e64 s[56:57], v1, v158
	v_or_b32_e32 v1, 43, v0
	v_cmp_gt_u32_e64 s[58:59], v1, v158
	v_or_b32_e32 v1, 16, v0
	v_cmp_gt_u32_e64 s[60:61], v1, v158
	v_or_b32_e32 v1, 48, v0
	v_cmp_gt_u32_e64 s[62:63], v1, v158
	v_or_b32_e32 v1, 17, v0
	v_cmp_gt_u32_e64 s[64:65], v1, v158
	v_or_b32_e32 v1, 49, v0
	v_cmp_gt_u32_e64 s[66:67], v1, v158
	v_or_b32_e32 v1, 18, v0
	v_cmp_gt_u32_e64 s[68:69], v1, v158
	v_or_b32_e32 v1, 50, v0
	v_cmp_gt_u32_e64 s[70:71], v1, v158
	v_or_b32_e32 v1, 19, v0
	v_cmp_gt_u32_e64 s[72:73], v1, v158
	v_or_b32_e32 v1, 51, v0
	v_cmp_gt_u32_e64 s[74:75], v1, v158
	v_or_b32_e32 v1, 24, v0
	v_cmp_gt_u32_e64 s[76:77], v1, v158
	v_or_b32_e32 v1, 56, v0
	v_cmp_gt_u32_e64 s[78:79], v1, v158
	v_or_b32_e32 v1, 25, v0
	v_cmp_gt_u32_e64 s[80:81], v1, v158
	v_or_b32_e32 v1, 57, v0
	v_cmp_gt_u32_e64 s[82:83], v1, v158
	v_or_b32_e32 v1, 26, v0
	v_cmp_gt_u32_e64 s[84:85], v1, v158
	v_or_b32_e32 v1, 58, v0
	v_mul_u32_u24_e32 v4, 0x90, v2
	v_and_or_b32 v8, v7, 2, v6
	v_cmp_gt_u32_e64 s[6:7], v0, v158
	v_cmp_lt_u32_e64 s[10:11], v0, v158
	v_cmp_gt_u32_e64 s[86:87], v1, v158
	v_or_b32_e32 v1, 27, v0
	v_or_b32_e32 v0, 59, v0
	v_lshlrev_b32_e32 v163, 5, v8
	v_add3_u32 v166, 0, v4, v5
	v_mov_b32_e32 v99, v98
	v_mov_b32_e32 v100, v98
	v_mov_b32_e32 v101, v98
	v_cmp_gt_u32_e64 s[88:89], v1, v158
	v_cmp_gt_u32_e64 s[90:91], v0, v158
	s_mov_b64 s[4:5], 0
	v_mov_b32_e32 v0, v160
	v_mov_b32_e32 v1, v160
	v_mov_b32_e32 v2, v160
	v_mov_b32_e32 v3, v160
	v_mov_b32_e32 v4, v160
	v_mov_b32_e32 v5, v160
	v_mov_b32_e32 v6, v160
	v_mov_b32_e32 v7, v160
	v_mov_b32_e32 v8, v160
	v_mov_b32_e32 v9, v160
	v_mov_b32_e32 v10, v160
	v_mov_b32_e32 v11, v160
	v_mov_b32_e32 v12, v160
	v_mov_b32_e32 v13, v160
	v_mov_b32_e32 v14, v160
	v_mov_b32_e32 v15, v160
	v_mov_b32_e32 v16, v33
	v_mov_b32_e32 v17, v33
	v_mov_b32_e32 v18, v33
	v_mov_b32_e32 v19, v33
	v_mov_b32_e32 v20, v33
	v_mov_b32_e32 v21, v33
	v_mov_b32_e32 v22, v33
	v_mov_b32_e32 v23, v33
	v_mov_b32_e32 v24, v33
	v_mov_b32_e32 v25, v33
	v_mov_b32_e32 v26, v33
	v_mov_b32_e32 v27, v33
	v_mov_b32_e32 v28, v33
	v_mov_b32_e32 v29, v33
	v_mov_b32_e32 v30, v33
	v_mov_b32_e32 v31, v33
	v_mov_b32_e32 v34, v32
	v_mov_b32_e32 v35, v32
	v_mov_b32_e32 v36, v32
	v_mov_b32_e32 v37, v32
	v_mov_b32_e32 v38, v32
	v_mov_b32_e32 v39, v32
	v_mov_b32_e32 v40, v32
	v_mov_b32_e32 v41, v32
	v_mov_b32_e32 v42, v32
	v_mov_b32_e32 v43, v32
	v_mov_b32_e32 v44, v32
	v_mov_b32_e32 v45, v32
	v_mov_b32_e32 v46, v32
	v_mov_b32_e32 v47, v32
	v_mov_b32_e32 v48, v32
	v_mov_b32_e32 v49, v32
	s_waitcnt vmcnt(1)
	ds_write_b128 v161, v[82:85]
	ds_write_b128 v161, v[90:93] offset:9216
	s_waitcnt vmcnt(0)
	ds_write_b128 v162, v[86:89] offset:36864
	ds_write_b128 v162, v[94:97] offset:45056
	s_waitcnt lgkmcnt(0)
	s_barrier
	s_and_b64 vcc, exec, s[24:25]
	s_cbranch_vccnz .Llb_5
	s_setprio 1
.Llb_5:
.LBB0_921:
	s_and_b32 s99, s4, 2
	s_mul_i32 s98, s99, 0x2400
	v_add_u32_e32 v168, s98, v166
	ds_read_b128 v[50:53], v168
	ds_read_b128 v[102:105], v168 offset:32
	ds_read_b128 v[66:69], v168 offset:4608
	ds_read_b128 v[106:109], v168 offset:4640
	ds_read_b128 v[110:113], v168 offset:64
	ds_read_b128 v[132:135], v168 offset:4672
	ds_read_b128 v[136:139], v168 offset:96
	ds_read_b128 v[140:143], v168 offset:4704
	s_add_u32 s94, s4, 2
	s_addc_u32 s95, s5, 0
	s_cmp_gt_i32 s94, s38
	s_cselect_b64 s[20:21], -1, 0
	s_cmp_le_i32 s94, s38
	s_cselect_b64 s[96:97], -1, 0
	s_cmp_lt_i32 s4, s23
	s_cselect_b64 s[0:1], -1, 0
	s_cselect_b64 s[92:93], 0, exec
	s_and_b64 vcc, exec, s[20:21]
	s_cbranch_vccnz .LBB0_925
	s_mov_b64 s[0:1], 0xc0000
	v_lshl_add_u64 v[154:155], v[154:155], 0, s[0:1]
	v_lshl_add_u64 v[156:157], v[156:157], 0, s[0:1]
	global_load_dwordx4 v[82:85], v[154:155], off
	global_load_dwordx4 v[86:89], v[156:157], off
	s_and_b64 vcc, exec, s[92:93]
	s_cbranch_vccnz .LBB0_924
	s_mov_b64 s[0:1], 0x60000
	v_lshl_add_u64 v[228:229], v[154:155], 0, s[0:1]
	global_load_dwordx4 v[90:93], v[228:229], off
	v_lshl_add_u64 v[228:229], v[156:157], 0, s[0:1]
	global_load_dwordx4 v[94:97], v[228:229], off

; #define LAS __attribute__((address_space(3)))
; __device__ __forceinline__ int crow(int r, int hi) { return (r & 3) + 8 * (r >> 2) + 4 * hi; }
; template <bool HAS_POST, class MaskF>
; __device__ __forceinline__ void attn_run(LAS unsigned char* lds, const bf16* Kg, const bf16* Vg, int pitch, int t0, int t1,
;                                          const bf16x8 (&qr)[4], f32x16& o0, f32x16& o1, f32x16& o2, MaskF& mf, const int wv) {
;     ...
;     if (t0 >= t1) return;
;     const int lrow = tid >> 3, lch = tid & 7;
;     const unsigned kwoff = lrow * 144 + lch * 16;
;     const unsigned vwoff = ATT_V0 + lrow * 128 + (((lch >> 1) ^ (((lrow >> 1) & 1) << 1)) * 32) + (lch & 1) * 16;
;     const bf16* kp = Kg + (size_t)(64 * t0 + lrow) * pitch + lch * 8;
;     const bf16* vp = Vg + (size_t)(64 * t0 + lrow) * pitch + lch * 8;
;     const size_t tstride = (size_t)64 * pitch;
;     const v4u z4 = (v4u){0u, 0u, 0u, 0u};
;     v4u kreg0 = *(const v4u*)kp, kreg1 = z4, vreg0 = *(const v4u*)vp, vreg1 = z4;
;     if (t0 + 1 < t1) { kreg1 = *(const v4u*)(kp + tstride); vreg1 = *(const v4u*)(vp + tstride); }
;     *(LAS v4u*)(lds + kwoff) = kreg0; *(LAS v4u*)(lds + KBUF + kwoff) = kreg1;
;     *(LAS v4u*)(lds + vwoff) = vreg0; *(LAS v4u*)(lds + VBUF + vwoff) = vreg1;
;     __syncthreads();
;     ACtx cx; cx.lds = lds; cx.kroff = r32 * 144 + hi * 16;
;     { const int gi = lane & 15, dsub = (lane >> 4) & 1, q4 = gi >> 2;
;       cx.vro0 = ATT_V0 + (4 * hi + q4) * 128 + (((0 + dsub) ^ (q4 & 2)) * 32) + (gi & 3) * 8;
;       cx.vro1 = ATT_V0 + (4 * hi + q4) * 128 + (((2 + dsub) ^ (q4 & 2)) * 32) + (gi & 3) * 8; }
;     if (wv >= 4) __builtin_amdgcn_s_setprio(1);
;     const short one_b = (r32 == 0) ? (short)0x3F80 : (short)0;
;     const bf16x8 ones = (bf16x8){one_b, one_b, one_b, one_b, one_b, one_b, one_b, one_b};
;     __device__ __forceinline__ void apply(int t, f32x16& p0, f32x16& p1) const {
;         if (t == c) {
; #pragma unroll
;             for (int r = 0; r < 16; ++r) { const int kv = crow(r, hi); if (kv > tq) p0[r] = NEGBIG; if (kv + 32 > tq) p1[r] = NEGBIG; }
;         } else if (t == c - 8) {
; #pragma unroll
;             for (int r = 0; r < 16; ++r) { const int kv = crow(r, hi); if (kv <= tq) p0[r] = NEGBIG; if (kv + 32 <= tq) p1[r] = NEGBIG; }
;         }
.LBB0_956:
	v_lshrrev_b32_e32 v3, 1, v3
	v_lshrrev_b32_e32 v5, 3, v0
	s_movk_i32 s0, 0x90
	v_bitop3_b32 v3, v3, v5, 2 bitop3:0x78
	v_lshlrev_b32_e32 v5, 4, v0
	v_mul_lo_u32 v4, v2, s0
	v_lshlrev_b32_e32 v2, 7, v2
	v_lshlrev_b32_e32 v3, 5, v3
	v_and_b32_e32 v5, 16, v5
	v_readlane_b32 s0, v253, 63
	v_or3_b32 v2, v2, v3, v5
	v_readlane_b32 s1, v254, 0
	v_add3_u32 v114, v4, v114, 0
	v_add_u32_e32 v203, 0, v2
	s_andn2_b64 vcc, exec, s[0:1]
	s_waitcnt lgkmcnt(0)
.LBB0_958:
	v_and_b32_e32 v2, 31, v0
	v_bfe_u32 v3, v0, 5, 1
	v_bfe_u32 v6, v0, 4, 1
	v_lshrrev_b32_e32 v7, 2, v1
	v_lshlrev_b32_e32 v0, 3, v0
	v_and_b32_e32 v205, 24, v0
	v_bitop3_b32 v0, v6, v7, 2 bitop3:0x72
	v_cmp_eq_u32_e32 vcc, 0, v2
	v_lshlrev_b32_e32 v1, 5, v1
	v_lshlrev_b32_e32 v206, 5, v0
	v_cndmask_b32_e32 v0, 0, v249, vcc
	s_mov_b32 s0, 0x5040100
	v_lshlrev_b32_e32 v5, 4, v3
	v_lshlrev_b32_e32 v3, 9, v3
	v_and_b32_e32 v1, 0x180, v1
	v_perm_b32 v148, v0, v0, s0
	v_lshlrev_b32_e32 v0, 2, v159
	v_add3_u32 v208, 0, v1, v3
	v_or_b32_e32 v1, 32, v0
	v_cmp_gt_u32_e64 s[8:9], v1, v158
	v_or_b32_e32 v1, 33, v0
	v_cmp_gt_u32_e64 s[12:13], v1, v158
	v_or_b32_e32 v1, 2, v0
	v_cmp_gt_u32_e64 s[14:15], v1, v158
	v_or_b32_e32 v1, 34, v0
	v_cmp_gt_u32_e64 s[16:17], v1, v158
	v_or_b32_e32 v1, 3, v0
	v_cmp_gt_u32_e64 s[40:41], v1, v158
	v_or_b32_e32 v1, 35, v0
	v_cmp_gt_u32_e64 s[42:43], v1, v158
	v_or_b32_e32 v1, 8, v0
	v_cmp_gt_u32_e64 s[44:45], v1, v158
	v_or_b32_e32 v1, 40, v0
	v_cmp_gt_u32_e64 s[46:47], v1, v158
	v_or_b32_e32 v1, 9, v0
	v_cmp_gt_u32_e64 s[48:49], v1, v158
	v_or_b32_e32 v1, 41, v0
	v_cmp_gt_u32_e64 s[50:51], v1, v158
	v_or_b32_e32 v1, 10, v0
	v_cmp_gt_u32_e64 s[52:53], v1, v158
	v_or_b32_e32 v1, 42, v0
	v_cmp_gt_u32_e64 s[54:55], v1, v158
	v_or_b32_e32 v1, 11, v0
	v_cmp_gt_u32_e64 s[56:57], v1, v158
	v_or_b32_e32 v1, 43, v0
	v_cmp_gt_u32_e64 s[58:59], v1, v158
	v_or_b32_e32 v1, 16, v0
	v_cmp_gt_u32_e64 s[60:61], v1, v158
	v_or_b32_e32 v1, 48, v0
	v_cmp_gt_u32_e64 s[62:63], v1, v158
	v_or_b32_e32 v1, 17, v0
	v_cmp_gt_u32_e64 s[64:65], v1, v158
	v_or_b32_e32 v1, 49, v0
	v_cmp_gt_u32_e64 s[66:67], v1, v158
	v_or_b32_e32 v1, 18, v0
	v_cmp_gt_u32_e64 s[68:69], v1, v158
	v_or_b32_e32 v1, 50, v0
	v_cmp_gt_u32_e64 s[70:71], v1, v158
	v_or_b32_e32 v1, 19, v0
	v_cmp_gt_u32_e64 s[72:73], v1, v158
	v_or_b32_e32 v1, 51, v0
	v_cmp_gt_u32_e64 s[74:75], v1, v158
	v_or_b32_e32 v1, 24, v0
	v_cmp_gt_u32_e64 s[76:77], v1, v158
	v_or_b32_e32 v1, 56, v0
	v_cmp_gt_u32_e64 s[78:79], v1, v158
	v_or_b32_e32 v1, 25, v0
	v_cmp_gt_u32_e64 s[80:81], v1, v158
	v_or_b32_e32 v1, 57, v0
	v_cmp_gt_u32_e64 s[82:83], v1, v158
	v_or_b32_e32 v1, 26, v0
	v_cmp_gt_u32_e64 s[84:85], v1, v158
	v_or_b32_e32 v1, 58, v0
	v_mul_u32_u24_e32 v4, 0x90, v2
	v_and_or_b32 v8, v7, 2, v6
	v_cmp_gt_u32_e64 s[6:7], v0, v158
	v_cmp_lt_u32_e64 s[10:11], v0, v158
	v_cmp_gt_u32_e64 s[86:87], v1, v158
	v_or_b32_e32 v1, 27, v0
	v_or_b32_e32 v0, 59, v0
	v_lshlrev_b32_e32 v204, 5, v8
	s_mov_b32 s96, 0
	v_add3_u32 v207, 0, v4, v5
	v_mov_b32_e32 v149, v148
	v_mov_b32_e32 v150, v148
	v_mov_b32_e32 v151, v148
	v_cmp_gt_u32_e64 s[88:89], v1, v158
	v_cmp_gt_u32_e64 s[90:91], v0, v158
	v_cmp_le_u32_e64 s[92:93], v0, v158
	v_mov_b32_e32 v0, v202
	v_mov_b32_e32 v1, v202
	v_mov_b32_e32 v2, v202
	v_mov_b32_e32 v3, v202
	v_mov_b32_e32 v4, v202
	v_mov_b32_e32 v5, v202
	v_mov_b32_e32 v6, v202
	v_mov_b32_e32 v7, v202
	v_mov_b32_e32 v8, v202
	v_mov_b32_e32 v9, v202
	v_mov_b32_e32 v10, v202
	v_mov_b32_e32 v11, v202
	v_mov_b32_e32 v12, v202
	v_mov_b32_e32 v13, v202
	v_mov_b32_e32 v14, v202
	v_mov_b32_e32 v15, v202
	v_mov_b32_e32 v16, v33
	v_mov_b32_e32 v17, v33
	v_mov_b32_e32 v18, v33
	v_mov_b32_e32 v19, v33
	v_mov_b32_e32 v20, v33
	v_mov_b32_e32 v21, v33
	v_mov_b32_e32 v22, v33
	v_mov_b32_e32 v23, v33
	v_mov_b32_e32 v24, v33
	v_mov_b32_e32 v25, v33
	v_mov_b32_e32 v26, v33
	v_mov_b32_e32 v27, v33
	v_mov_b32_e32 v28, v33
	v_mov_b32_e32 v29, v33
	v_mov_b32_e32 v30, v33
	v_mov_b32_e32 v31, v33
	v_mov_b32_e32 v34, v32
	v_mov_b32_e32 v35, v32
	v_mov_b32_e32 v36, v32
	v_mov_b32_e32 v37, v32
	v_mov_b32_e32 v38, v32
	v_mov_b32_e32 v39, v32
	v_mov_b32_e32 v40, v32
	v_mov_b32_e32 v41, v32
	v_mov_b32_e32 v42, v32
	v_mov_b32_e32 v43, v32
	v_mov_b32_e32 v44, v32
	v_mov_b32_e32 v45, v32
	v_mov_b32_e32 v46, v32
	v_mov_b32_e32 v47, v32
	v_mov_b32_e32 v48, v32
	v_mov_b32_e32 v49, v32
	s_waitcnt vmcnt(1)
	ds_write_b128 v114, v[132:135]
	ds_write_b128 v114, v[140:143] offset:9216
	s_waitcnt vmcnt(0)
	ds_write_b128 v203, v[136:139] offset:36864
	ds_write_b128 v203, v[144:147] offset:45056
	s_waitcnt lgkmcnt(0)
	s_barrier
	s_and_b64 vcc, exec, s[24:25]
	s_cbranch_vccnz .Llb_4
	s_setprio 1
.Llb_4:
	s_branch .LBB0_960
.LBB0_959:
	s_add_i32 s96, s96, 2
	s_add_i32 s0, s3, s96
	s_add_i32 s0, s0, -8
	s_cmp_gt_i32 s0, s38
	s_waitcnt lgkmcnt(0)
	s_barrier
	s_cbranch_scc1 .LBB0_993

; #define LAS __attribute__((address_space(3)))
; template <bool HAS_POST, class MaskF>
; __device__ __forceinline__ void attn_run(LAS unsigned char* lds, const bf16* Kg, const bf16* Vg, int pitch, int t0, int t1,
;                                          const bf16x8 (&qr)[4], f32x16& o0, f32x16& o1, f32x16& o2, MaskF& mf, const int wv) {
;     ...
;     if (t0 >= t1) return;
;     const int lrow = tid >> 3, lch = tid & 7;
;     const unsigned kwoff = lrow * 144 + lch * 16;
;     const unsigned vwoff = ATT_V0 + lrow * 128 + (((lch >> 1) ^ (((lrow >> 1) & 1) << 1)) * 32) + (lch & 1) * 16;
;     const bf16* kp = Kg + (size_t)(64 * t0 + lrow) * pitch + lch * 8;
;     const bf16* vp = Vg + (size_t)(64 * t0 + lrow) * pitch + lch * 8;
;     const size_t tstride = (size_t)64 * pitch;
;     const v4u z4 = (v4u){0u, 0u, 0u, 0u};
;     v4u kreg0 = *(const v4u*)kp, kreg1 = z4, vreg0 = *(const v4u*)vp, vreg1 = z4;
;     if (t0 + 1 < t1) { kreg1 = *(const v4u*)(kp + tstride); vreg1 = *(const v4u*)(vp + tstride); }
;     *(LAS v4u*)(lds + kwoff) = kreg0; *(LAS v4u*)(lds + KBUF + kwoff) = kreg1;
;     *(LAS v4u*)(lds + vwoff) = vreg0; *(LAS v4u*)(lds + VBUF + vwoff) = vreg1;
;     __syncthreads();
;     ACtx cx; cx.lds = lds; cx.kroff = r32 * 144 + hi * 16;
;     { const int gi = lane & 15, dsub = (lane >> 4) & 1, q4 = gi >> 2;
;       cx.vro0 = ATT_V0 + (4 * hi + q4) * 128 + (((0 + dsub) ^ (q4 & 2)) * 32) + (gi & 3) * 8;
;       cx.vro1 = ATT_V0 + (4 * hi + q4) * 128 + (((2 + dsub) ^ (q4 & 2)) * 32) + (gi & 3) * 8; }
;     if (wv >= 4) __builtin_amdgcn_s_setprio(1);
;     const short one_b = (r32 == 0) ? (short)0x3F80 : (short)0;
;     const bf16x8 ones = (bf16x8){one_b, one_b, one_b, one_b, one_b, one_b, one_b, one_b};
.LBB0_1005:
	v_and_b32_e32 v0, 31, v4
	v_cmp_eq_u32_e32 vcc, 0, v0
	v_mul_u32_u24_e32 v6, 0x90, v0
	s_mov_b32 s0, 0x5040100
	v_cndmask_b32_e32 v0, 0, v249, vcc
	v_bfe_u32 v1, v4, 5, 1
	v_bfe_u32 v8, v4, 4, 1
	v_lshrrev_b32_e32 v9, 2, v5
	v_lshlrev_b32_e32 v5, 5, v5
	v_lshlrev_b32_e32 v4, 3, v4
	v_perm_b32 v98, v0, v0, s0
	v_add3_u32 v0, v153, v3, v2
	s_movk_i32 s0, 0x104
	v_lshlrev_b32_e32 v7, 4, v1
	v_lshlrev_b32_e32 v1, 9, v1
	v_and_b32_e32 v5, 0x180, v5
	v_and_or_b32 v10, v9, 2, v8
	v_and_b32_e32 v165, 24, v4
	v_bitop3_b32 v4, v8, v9, 2 bitop3:0x72
	v_mul_lo_u32 v0, v0, s0
	s_mov_b32 s16, 2
	v_lshlrev_b32_e32 v164, 5, v10
	v_lshlrev_b32_e32 v166, 5, v4
	s_mov_b32 s17, 0
	v_add3_u32 v167, 0, v6, v7
	v_mov_b32_e32 v99, v98
	v_mov_b32_e32 v100, v98
	v_mov_b32_e32 v101, v98
	v_add3_u32 v168, 0, v5, v1
	v_lshlrev_b32_e32 v169, 2, v159
	v_add_u32_e32 v170, 0, v0
	v_lshl_add_u32 v171, v159, 6, v242
	v_or_b32_e32 v172, 20, v159
	v_mov_b32_e32 v34, v32
	v_mov_b32_e32 v35, v32
	v_mov_b32_e32 v36, v32
	v_mov_b32_e32 v37, v32
	v_mov_b32_e32 v38, v32
	v_mov_b32_e32 v39, v32
	v_mov_b32_e32 v40, v32
	v_mov_b32_e32 v41, v32
	v_mov_b32_e32 v42, v32
	v_mov_b32_e32 v43, v32
	v_mov_b32_e32 v44, v32
	v_mov_b32_e32 v45, v32
	v_mov_b32_e32 v46, v32
	v_mov_b32_e32 v47, v32
	v_mov_b32_e32 v48, v32
	v_mov_b32_e32 v49, v32
	v_mov_b32_e32 v0, v162
	v_mov_b32_e32 v1, v162
	v_mov_b32_e32 v2, v162
	v_mov_b32_e32 v3, v162
	v_mov_b32_e32 v4, v162
	v_mov_b32_e32 v5, v162
	v_mov_b32_e32 v6, v162
	v_mov_b32_e32 v7, v162
	v_mov_b32_e32 v8, v162
	v_mov_b32_e32 v9, v162
	v_mov_b32_e32 v10, v162
	v_mov_b32_e32 v11, v162
	v_mov_b32_e32 v12, v162
	v_mov_b32_e32 v13, v162
	v_mov_b32_e32 v14, v162
	v_mov_b32_e32 v15, v162
	v_mov_b32_e32 v16, v161
	v_mov_b32_e32 v17, v161
	v_mov_b32_e32 v18, v161
	v_mov_b32_e32 v19, v161
	v_mov_b32_e32 v20, v161
	v_mov_b32_e32 v21, v161
	v_mov_b32_e32 v22, v161
	v_mov_b32_e32 v23, v161
	v_mov_b32_e32 v24, v161
	v_mov_b32_e32 v25, v161
	v_mov_b32_e32 v26, v161
	v_mov_b32_e32 v27, v161
	v_mov_b32_e32 v28, v161
	v_mov_b32_e32 v29, v161
	v_mov_b32_e32 v30, v161
	v_mov_b32_e32 v31, v161
	s_waitcnt vmcnt(1)
	ds_write_b128 v114, v[82:85]
	ds_write_b128 v114, v[90:93] offset:9216
	s_waitcnt vmcnt(0)
	ds_write_b128 v163, v[86:89] offset:36864
	ds_write_b128 v163, v[94:97] offset:45056
	s_waitcnt lgkmcnt(0)
	s_barrier
	global_load_dwordx4 v[212:215], v[210:211], off
	global_load_dwordx4 v[216:219], v[210:211], off offset:32
	global_load_dwordx4 v[220:223], v[210:211], off offset:64
	global_load_dwordx4 v[224:227], v[210:211], off offset:96
	s_and_b64 vcc, exec, s[24:25]
	s_cbranch_vccnz .Llb_3
	s_setprio 1
.Llb_3:
	s_branch .LBB0_1007
.LBB0_1006:
	v_add_u32_e32 v170, 0x80, v170
	v_add_u32_e32 v171, 0x800, v171
	s_addk_i32 s17, 0x80
	v_add_u32_e32 v172, 32, v172
	s_add_i32 s16, s16, 2
	s_and_b64 vcc, exec, s[12:13]
	s_waitcnt lgkmcnt(0)
	s_barrier
	s_cbranch_vccnz .LBB0_1033

; template <bool HAS_POST, class MaskF>
; __device__ __forceinline__ void attn_run(LAS unsigned char* lds, const bf16* Kg, const bf16* Vg, int pitch, int t0, int t1,
;                                          const bf16x8 (&qr)[4], f32x16& o0, f32x16& o1, f32x16& o2, MaskF& mf, const int wv) {
;     ...
;     for (int ts = t0; ts < t1; ts += 2) {
;         const int cur = ((ts - t0) >> 1) & 1;
;         const bool more = (ts + 2 < t1), more2 = (ts + 3 < t1);
;         if (more) { kp += 2 * tstride; kreg0 = *(const v4u*)kp; vp += 2 * tstride; vreg0 = *(const v4u*)vp;
;             if (more2) { kreg1 = *(const v4u*)(kp + tstride); vreg1 = *(const v4u*)(vp + tstride); } }
.Llb_2:
.LBB0_1077:
	s_and_b32 s99, s4, 2
	s_mul_i32 s98, s99, 0x2400
	v_add_u32_e32 v168, s98, v166
	ds_read_b128 v[50:53], v168
	ds_read_b128 v[102:105], v168 offset:32
	ds_read_b128 v[66:69], v168 offset:4608
	ds_read_b128 v[106:109], v168 offset:4640
	ds_read_b128 v[110:113], v168 offset:64
	ds_read_b128 v[132:135], v168 offset:4672
	ds_read_b128 v[136:139], v168 offset:96
	ds_read_b128 v[140:143], v168 offset:4704
	s_add_u32 s94, s4, 2
	s_addc_u32 s95, s5, 0
	s_cmp_gt_i32 s94, s39
	s_cselect_b64 s[20:21], -1, 0
	s_cmp_le_i32 s94, s39
	s_cselect_b64 s[96:97], -1, 0
	s_cmp_lt_i32 s4, s27
	s_cselect_b64 s[0:1], -1, 0
	s_cselect_b64 s[92:93], 0, exec
	s_and_b64 vcc, exec, s[20:21]
	s_cbranch_vccnz .LBB0_1081
	s_mov_b64 s[0:1], 0xc0000
	v_lshl_add_u64 v[154:155], v[154:155], 0, s[0:1]
	v_lshl_add_u64 v[156:157], v[156:157], 0, s[0:1]
	global_load_dwordx4 v[82:85], v[154:155], off
	global_load_dwordx4 v[86:89], v[156:157], off
	s_and_b64 vcc, exec, s[92:93]
	s_cbranch_vccnz .LBB0_1080
	s_mov_b64 s[0:1], 0x60000
	v_lshl_add_u64 v[228:229], v[154:155], 0, s[0:1]
	global_load_dwordx4 v[90:93], v[228:229], off
	v_lshl_add_u64 v[228:229], v[156:157], 0, s[0:1]
	global_load_dwordx4 v[94:97], v[228:229], off

; template <bool HAS_POST, class MaskF>
; __device__ __forceinline__ void attn_run(LAS unsigned char* lds, const bf16* Kg, const bf16* Vg, int pitch, int t0, int t1,
;                                          const bf16x8 (&qr)[4], f32x16& o0, f32x16& o1, f32x16& o2, MaskF& mf, const int wv) {
;     ...
;     for (int ts = t0; ts < t1; ts += 2) {
;         const int cur = ((ts - t0) >> 1) & 1;
;         const bool more = (ts + 2 < t1), more2 = (ts + 3 < t1);
;     ...
;         __syncthreads();
.Llb_1:
	s_branch .LBB0_1116
.LBB0_1115:
	s_add_i32 s96, s96, 2
	s_add_i32 s0, s35, s96
	s_add_i32 s0, s0, -8
	s_cmp_gt_i32 s0, s39
	s_waitcnt lgkmcnt(0)
	s_barrier
	s_cbranch_scc1 .LBB0_1149

; __device__ __forceinline__ void moba_unit(const int wv, LAS unsigned char* lds, int b, int h, int qb, const bf16* Y, const float* kmean_l, bf16* OG) {
;     ...
; #pragma unroll 1
;         for (int it = 0; it < 3; ++it) {
;             float best = -3.0e38f; int bi = -1;
; #pragma unroll
;             for (int n = 0; n < 16; ++n) { const bool ok = (n < qb) && !((mask >> n) & 1u); const float cand = ok ? ga[n] : -3.0e38f; if (cand > best) { best = cand; bi = n; } }
;             if (bi >= 0) mask |= (1u << bi);
;         }
;         if (half == 0) selm[ql] = mask;
;     }
;     __syncthreads();
;     MobaMask mf; mf.qb = qb; mf.qrel = 32 * wid + r32; mf.hi = hi; mf.wq0 = 32 * wv; mf.sel = selm[32 * wid + r32];
.LBB0_1159:
	v_and_b32_e32 v18, 1, v17
	v_cmp_eq_u32_e64 s[6:7], 0, v18
	s_and_b64 s[6:7], s[4:5], s[6:7]
	v_and_b32_e32 v20, 2, v17
	v_cndmask_b32_e64 v18, v245, v1, s[6:7]
	v_cmp_nlt_f32_e64 s[6:7], s1, v18
	s_add_i32 s0, s0, -1
	s_nop 0
	v_cndmask_b32_e64 v18, v18, v245, s[6:7]
	v_cndmask_b32_e64 v19, 0, -1, s[6:7]
	v_cmp_eq_u32_e64 s[6:7], 0, v20
	s_and_b64 s[6:7], s[14:15], s[6:7]
	s_nop 0
	v_cndmask_b32_e64 v20, v245, v7, s[6:7]
	v_cmp_gt_f32_e64 s[6:7], v20, v18
	s_nop 1
	v_cndmask_b32_e64 v18, v18, v20, s[6:7]
	v_and_b32_e32 v20, 4, v17
	v_cndmask_b32_e64 v19, v19, 1, s[6:7]
	v_cmp_eq_u32_e64 s[6:7], 0, v20
	s_and_b64 s[6:7], s[16:17], s[6:7]
	s_nop 0
	v_cndmask_b32_e64 v20, v245, v11, s[6:7]
	v_cmp_gt_f32_e64 s[6:7], v20, v18
	s_nop 1
	v_cndmask_b32_e64 v18, v18, v20, s[6:7]
	v_and_b32_e32 v20, 8, v17
	v_cndmask_b32_e64 v19, v19, 2, s[6:7]
	v_cmp_eq_u32_e64 s[6:7], 0, v20
	s_and_b64 s[6:7], s[18:19], s[6:7]
	s_nop 0
	v_cndmask_b32_e64 v20, v245, v13, s[6:7]
	v_cmp_gt_f32_e64 s[6:7], v20, v18
	s_nop 1
	v_cndmask_b32_e64 v18, v18, v20, s[6:7]
	v_and_b32_e32 v20, 16, v17
	v_cndmask_b32_e64 v19, v19, 3, s[6:7]
	v_cmp_eq_u32_e64 s[6:7], 0, v20
	s_and_b64 s[6:7], s[20:21], s[6:7]
	s_nop 0
	v_cndmask_b32_e64 v20, v245, v14, s[6:7]
	v_cmp_gt_f32_e64 s[6:7], v20, v18
	s_nop 1
	v_cndmask_b32_e64 v18, v18, v20, s[6:7]
	v_and_b32_e32 v20, 32, v17
	v_cndmask_b32_e64 v19, v19, 4, s[6:7]
	v_cmp_eq_u32_e64 s[6:7], 0, v20
	s_and_b64 s[6:7], s[30:31], s[6:7]
	s_nop 0
	v_cndmask_b32_e64 v20, v245, v15, s[6:7]
	v_cmp_gt_f32_e64 s[6:7], v20, v18
	s_nop 1
	v_cndmask_b32_e64 v18, v18, v20, s[6:7]
	v_and_b32_e32 v20, 64, v17
	v_cndmask_b32_e64 v19, v19, 5, s[6:7]
	v_cmp_eq_u32_e64 s[6:7], 0, v20
	s_and_b64 s[6:7], s[38:39], s[6:7]
	s_nop 0
	v_cndmask_b32_e64 v20, v245, v16, s[6:7]
	v_cmp_gt_f32_e64 s[6:7], v20, v18
	s_nop 1
	v_cndmask_b32_e64 v18, v18, v20, s[6:7]
	v_and_b32_e32 v20, 0x80, v17
	v_cndmask_b32_e64 v19, v19, 6, s[6:7]
	v_cmp_eq_u32_e64 s[6:7], 0, v20
	s_and_b64 s[6:7], s[40:41], s[6:7]
	s_nop 0
	v_cndmask_b32_e64 v20, v245, v3, s[6:7]
	v_cmp_gt_f32_e64 s[6:7], v20, v18
	s_nop 1
	v_cndmask_b32_e64 v18, v18, v20, s[6:7]
	v_and_b32_e32 v20, 0x100, v17
	v_cndmask_b32_e64 v19, v19, 7, s[6:7]
	v_cmp_eq_u32_e64 s[6:7], 0, v20
	s_and_b64 s[6:7], s[42:43], s[6:7]
	s_nop 0
	v_cndmask_b32_e64 v20, v245, v6, s[6:7]
	v_cmp_gt_f32_e64 s[6:7], v20, v18
	s_nop 1
	v_cndmask_b32_e64 v18, v18, v20, s[6:7]
	v_and_b32_e32 v20, 0x200, v17
	v_cndmask_b32_e64 v19, v19, 8, s[6:7]
	v_cmp_eq_u32_e64 s[6:7], 0, v20
	s_and_b64 s[6:7], s[44:45], s[6:7]
	s_nop 0
	v_cndmask_b32_e64 v20, v245, v10, s[6:7]
	v_cmp_gt_f32_e64 s[6:7], v20, v18
	s_nop 1
	v_cndmask_b32_e64 v18, v18, v20, s[6:7]
	v_and_b32_e32 v20, 0x400, v17
	v_cndmask_b32_e64 v19, v19, 9, s[6:7]
	v_cmp_eq_u32_e64 s[6:7], 0, v20
	s_and_b64 s[6:7], s[46:47], s[6:7]
	s_nop 0
	v_cndmask_b32_e64 v20, v245, v8, s[6:7]
	v_cmp_gt_f32_e64 s[6:7], v20, v18
	s_nop 1
	v_cndmask_b32_e64 v18, v18, v20, s[6:7]
	v_and_b32_e32 v20, 0x800, v17
	v_cndmask_b32_e64 v19, v19, 10, s[6:7]
	v_cmp_eq_u32_e64 s[6:7], 0, v20
	s_and_b64 s[6:7], s[48:49], s[6:7]
	s_nop 0
	v_cndmask_b32_e64 v20, v245, v9, s[6:7]
	v_cmp_gt_f32_e64 s[6:7], v20, v18
	s_nop 1
	v_cndmask_b32_e64 v18, v18, v20, s[6:7]
	v_and_b32_e32 v20, 0x1000, v17
	v_cndmask_b32_e64 v19, v19, 11, s[6:7]
	v_cmp_eq_u32_e64 s[6:7], 0, v20
	s_and_b64 s[6:7], s[50:51], s[6:7]
	s_nop 0
	v_cndmask_b32_e64 v20, v245, v4, s[6:7]
	v_cmp_gt_f32_e64 s[6:7], v20, v18
	s_nop 1
	v_cndmask_b32_e64 v18, v18, v20, s[6:7]
	v_and_b32_e32 v20, 0x2000, v17
	v_cndmask_b32_e64 v19, v19, 12, s[6:7]
	v_cmp_eq_u32_e64 s[6:7], 0, v20
	s_and_b64 s[6:7], s[52:53], s[6:7]
	s_nop 0
	v_cndmask_b32_e64 v20, v245, v5, s[6:7]
	v_cmp_gt_f32_e64 s[6:7], v20, v18
	s_nop 1
	v_cndmask_b32_e64 v18, v18, v20, s[6:7]
	v_and_b32_e32 v20, 0x4000, v17
	v_cndmask_b32_e64 v19, v19, 13, s[6:7]
	v_cmp_eq_u32_e64 s[6:7], 0, v20
	s_and_b64 s[6:7], s[54:55], s[6:7]
	s_cmp_lg_u32 s0, 0
	v_cndmask_b32_e64 v20, v245, v2, s[6:7]
	v_cmp_gt_f32_e64 s[6:7], v20, v18
	s_nop 1
	v_cndmask_b32_e64 v18, v18, v20, s[6:7]
	v_cndmask_b32_e64 v19, v19, 14, s[6:7]
	v_cmp_ngt_f32_e64 s[6:7], s1, v18
	s_nop 1
	v_cndmask_b32_e64 v18, 15, v19, s[6:7]
	v_lshlrev_b32_e64 v19, v18, 1
	v_cmp_lt_i32_e64 s[6:7], -1, v18
	s_nop 1
	v_cndmask_b32_e64 v18, 0, v19, s[6:7]
	v_or_b32_e32 v17, v18, v17
	s_cbranch_scc1 .LBB0_1159
	s_and_saveexec_b64 s[4:5], vcc
	v_lshl_add_u32 v1, v0, 2, 0
	v_add_u32_e32 v1, 0x21400, v1
	ds_write_b32 v1, v17
	s_or_b64 exec, exec, s[4:5]
	v_and_b32_e32 v2, 0xffffffe0, v0
	s_movk_i32 s1, 0xffe0
	v_bfi_b32 v158, s1, v0, v12
	v_ashrrev_i32_e32 v3, 31, v2
	v_and_b32_e32 v1, 31, v12
	v_lshl_add_u32 v0, v158, 2, 0
	v_lshl_add_u64 v[112:113], s[10:11], 0, v[2:3]
	s_lshl_b32 s0, s12, 6
	v_add_u32_e32 v0, 0x21400, v0
	v_or_b32_e32 v112, v112, v1
	v_readlane_b32 s6, v254, 27
	s_and_b32 s0, s0, 0x3c0
	s_waitcnt lgkmcnt(0)
	s_barrier
; #define LAS __attribute__((address_space(3)))
; template <bool HAS_POST, class MaskF>
; __device__ __forceinline__ void attn_run(LAS unsigned char* lds, const bf16* Kg, const bf16* Vg, int pitch, int t0, int t1,
;                                          const bf16x8 (&qr)[4], f32x16& o0, f32x16& o1, f32x16& o2, MaskF& mf, const int wv) {
;     ...
;     if (t0 >= t1) return;
;     const int lrow = tid >> 3, lch = tid & 7;
;     const unsigned kwoff = lrow * 144 + lch * 16;
;     const unsigned vwoff = ATT_V0 + lrow * 128 + (((lch >> 1) ^ (((lrow >> 1) & 1) << 1)) * 32) + (lch & 1) * 16;
;     const bf16* kp = Kg + (size_t)(64 * t0 + lrow) * pitch + lch * 8;
;     const bf16* vp = Vg + (size_t)(64 * t0 + lrow) * pitch + lch * 8;
;     const size_t tstride = (size_t)64 * pitch;
;     const v4u z4 = (v4u){0u, 0u, 0u, 0u};
;     v4u kreg0 = *(const v4u*)kp, kreg1 = z4, vreg0 = *(const v4u*)vp, vreg1 = z4;
;     if (t0 + 1 < t1) { kreg1 = *(const v4u*)(kp + tstride); vreg1 = *(const v4u*)(vp + tstride); }
;     *(LAS v4u*)(lds + kwoff) = kreg0; *(LAS v4u*)(lds + KBUF + kwoff) = kreg1;
;     *(LAS v4u*)(lds + vwoff) = vreg0; *(LAS v4u*)(lds + VBUF + vwoff) = vreg1;
;     __syncthreads();
;     ACtx cx; cx.lds = lds; cx.kroff = r32 * 144 + hi * 16;
;     { const int gi = lane & 15, dsub = (lane >> 4) & 1, q4 = gi >> 2;
;       cx.vro0 = ATT_V0 + (4 * hi + q4) * 128 + (((0 + dsub) ^ (q4 & 2)) * 32) + (gi & 3) * 8;
;       cx.vro1 = ATT_V0 + (4 * hi + q4) * 128 + (((2 + dsub) ^ (q4 & 2)) * 32) + (gi & 3) * 8; }
; __device__ __forceinline__ void moba_unit(const int wv, LAS unsigned char* lds, int b, int h, int qb, const bf16* Y, const float* kmean_l, bf16* OG) {
;     ...
;     MobaMask mf; mf.qb = qb; mf.qrel = 32 * wid + r32; mf.hi = hi; mf.wq0 = 32 * wv; mf.sel = selm[32 * wid + r32];
;     const size_t row = rowblk + 32 * wid + r32;
;     bf16x8 qr[4]; load_q(Y + row * MOBA_LDY + h * 64, hi, qr);
;     f32x16 o0 = zero16(), o1 = zero16(), o2 = zero16();
;     const bf16* Kg = Y + (size_t)b * T * MOBA_LDY + 1024 + h * 64;
;     attn_run<false>(lds, Kg, Kg + 1024, MOBA_LDY, 0, 4 * qb + 4, qr, o0, o1, o2, mf, wv);
	ds_read_b32 v159, v0
	v_lshlrev_b64 v[0:1], 13, v[112:113]
	v_readlane_b32 s7, v254, 28
	v_readlane_b32 s4, v254, 9
	v_bfe_u32 v48, v12, 5, 1
	v_lshl_add_u64 v[152:153], s[6:7], 0, v[0:1]
	v_readlane_b32 s5, v254, 10
	s_lshl_b32 s4, s0, 1
	v_lshlrev_b32_e32 v114, 4, v48
	v_lshl_add_u64 v[0:1], v[152:153], 0, s[4:5]
	v_lshl_add_u64 v[0:1], v[0:1], 0, v[114:115]
	global_load_dwordx4 v[80:83], v[0:1], off
	global_load_dwordx4 v[84:87], v[0:1], off offset:32
	global_load_dwordx4 v[88:91], v[0:1], off offset:64
	global_load_dwordx4 v[92:95], v[0:1], off offset:96
	v_add_co_u32_e32 v172, vcc, 0x1800, v0
	s_nop 1
	v_addc_co_u32_e32 v173, vcc, 0, v1, vcc
	v_mov_b32_e32 v16, v115
	v_mov_b32_e32 v0, v115
	v_mov_b32_e32 v32, v115
	s_lshl_b64 s[0:1], s[8:9], 25
	v_mbcnt_lo_u32_b32 v49, -1, 0
	v_mbcnt_hi_u32_b32 v49, -1, v49
	s_add_u32 s0, s6, s0
	v_bfe_u32 v3, v49, 1, 2
	v_lshrrev_b32_e32 v4, 3, v49
	v_add_u32_e32 v50, s83, v49
	v_bitop3_b32 v3, v3, v4, 2 bitop3:0x78
	s_addc_u32 s1, s7, s1
	v_writelane_b32 v254, s4, 9
	v_ashrrev_i32_e32 v2, 3, v50
	v_lshlrev_b32_e32 v7, 5, v3
	v_lshlrev_b32_e32 v3, 4, v49
	v_writelane_b32 v254, s5, 10
	s_add_u32 s0, s0, s4
	v_and_b32_e32 v1, 7, v49
	s_movk_i32 s4, 0x90
	v_and_b32_e32 v8, 16, v3
	v_ashrrev_i32_e32 v3, 31, v2
	s_addc_u32 s1, s1, 0
	v_mul_lo_u32 v6, v2, s4
	v_lshlrev_b32_e32 v114, 4, v1
	v_lshlrev_b32_e32 v1, 7, v2
	v_lshlrev_b64 v[2:3], 13, v[2:3]
	v_lshl_add_u64 v[2:3], s[0:1], 0, v[2:3]
	v_lshl_add_u64 v[2:3], v[2:3], 0, v[114:115]
	s_mov_b64 s[0:1], 0x800
	v_lshl_add_u64 v[154:155], v[2:3], 0, s[0:1]
	s_mov_b32 s0, 0x80000
	v_add_co_u32_e32 v4, vcc, s0, v2
	s_mov_b32 s0, 0x81000
	s_nop 0
	v_addc_co_u32_e32 v5, vcc, 0, v3, vcc
	global_load_dwordx4 v[96:99], v[2:3], off offset:2048
	global_load_dwordx4 v[100:103], v[154:155], off offset:2048
	v_add_co_u32_e32 v2, vcc, s0, v2
	global_load_dwordx4 v[104:107], v[4:5], off offset:2048
	s_nop 0
	v_addc_co_u32_e32 v3, vcc, 0, v3, vcc
	global_load_dwordx4 v[108:111], v[2:3], off
	v_readlane_b32 s0, v253, 63
	v_or3_b32 v1, v1, v7, v8
	v_readlane_b32 s1, v254, 0
	v_add3_u32 v160, v6, v114, 0
	v_add_u32_e32 v161, 0, v1
	s_andn2_b64 vcc, exec, s[0:1]
	s_waitcnt lgkmcnt(0)
.LBB0_1164:
	v_and_b32_e32 v51, 31, v49
	v_bfe_u32 v52, v49, 5, 1
	v_bfe_u32 v55, v49, 4, 1
	v_lshrrev_b32_e32 v56, 2, v50
	v_lshlrev_b32_e32 v49, 3, v49
	s_mov_b64 s[0:1], 0x800
	v_and_b32_e32 v163, 24, v49
	v_bitop3_b32 v49, v55, v56, 2 bitop3:0x72
	v_cmp_eq_u32_e32 vcc, 0, v51
	v_lshl_add_u64 v[156:157], v[154:155], 0, s[0:1]
	v_lshlrev_b32_e32 v50, 5, v50
	v_lshlrev_b32_e32 v164, 5, v49
	v_cndmask_b32_e32 v49, 0, v249, vcc
	s_mov_b32 s0, 0x5040100
	s_lshl_b32 s34, s33, 2
	v_mul_u32_u24_e32 v53, 0x90, v51
	v_lshlrev_b32_e32 v54, 4, v52
	v_lshlrev_b32_e32 v52, 9, v52
	v_and_b32_e32 v50, 0x180, v50
	v_and_or_b32 v57, v56, 2, v55
	v_perm_b32 v116, v49, v49, s0
	v_lshlrev_b32_e32 v114, 3, v48
	v_mov_b32_e32 v17, v16
	v_mov_b32_e32 v18, v16
	v_mov_b32_e32 v19, v16
	v_mov_b32_e32 v20, v16
	v_mov_b32_e32 v21, v16
	v_mov_b32_e32 v22, v16
	v_mov_b32_e32 v23, v16
	v_mov_b32_e32 v24, v16
	v_mov_b32_e32 v25, v16
	v_mov_b32_e32 v26, v16
	v_mov_b32_e32 v27, v16
	v_mov_b32_e32 v28, v16
	v_mov_b32_e32 v29, v16
	v_mov_b32_e32 v30, v16
	v_mov_b32_e32 v31, v16
	v_mov_b32_e32 v1, v0
	v_mov_b32_e32 v2, v0
	v_mov_b32_e32 v3, v0
	v_mov_b32_e32 v4, v0
	v_mov_b32_e32 v5, v0
	v_mov_b32_e32 v6, v0
	v_mov_b32_e32 v7, v0
	v_mov_b32_e32 v8, v0
	v_mov_b32_e32 v9, v0
	v_mov_b32_e32 v10, v0
	v_mov_b32_e32 v11, v0
	v_mov_b32_e32 v12, v0
	v_mov_b32_e32 v13, v0
	v_mov_b32_e32 v14, v0
	v_mov_b32_e32 v15, v0
	v_mov_b32_e32 v33, v32
	v_mov_b32_e32 v34, v32
	v_mov_b32_e32 v35, v32
	v_mov_b32_e32 v36, v32
	v_mov_b32_e32 v37, v32
	v_mov_b32_e32 v38, v32
	v_mov_b32_e32 v39, v32
	v_mov_b32_e32 v40, v32
	v_mov_b32_e32 v41, v32
	v_mov_b32_e32 v42, v32
	v_mov_b32_e32 v43, v32
	v_mov_b32_e32 v44, v32
	v_mov_b32_e32 v45, v32
	v_mov_b32_e32 v46, v32
	v_mov_b32_e32 v47, v32
	s_add_i32 s35, s34, 4
	v_lshlrev_b32_e32 v162, 5, v57
	v_add3_u32 v165, 0, v53, v54
	v_mov_b32_e32 v117, v116
	v_mov_b32_e32 v118, v116
	v_mov_b32_e32 v119, v116
	v_add3_u32 v166, 0, v50, v52
	v_lshlrev_b32_e32 v167, 2, v48
	s_mov_b32 s36, 64
	s_mov_b32 s37, 1
	s_waitcnt vmcnt(3)
	ds_write_b128 v160, v[96:99]
	s_waitcnt vmcnt(1)
	ds_write_b128 v160, v[104:107] offset:9216
	ds_write_b128 v161, v[100:103] offset:36864
	s_waitcnt vmcnt(0)
	ds_write_b128 v161, v[108:111] offset:45056
	s_waitcnt lgkmcnt(0)
	s_barrier
	global_load_dwordx4 v[198:201], v[172:173], off
	global_load_dwordx4 v[202:205], v[172:173], off offset:32
	global_load_dwordx4 v[206:209], v[172:173], off offset:64
	global_load_dwordx4 v[210:213], v[172:173], off offset:96
	s_and_b64 vcc, exec, s[24:25]
	s_cbranch_vccnz .Llb_0
	s_setprio 1
.Llb_0:
	s_branch .LBB0_1166
.LBB0_1165:
	s_addk_i32 s36, 0x80
	s_add_i32 s37, s37, 2
	s_cmp_lt_u32 s58, s35
	s_waitcnt lgkmcnt(0)
	s_barrier
	s_cbranch_scc0 .LBB0_1155
